# GEMM work-queue to tile mapping: MLP2 keeps all 8 column tiles of a row panel in one XCD (NP 4->1), MLP1 NP 4->2; fewer cross-XCD re-reads of the activation panels
# speedup vs baseline: 1.0120x; 1.0120x over previous
.Lpf_have_m1:
	s_movk_i32 s34, 0x120
	s_waitcnt vmcnt(0)
	v_cmp_gt_i32_e32 vcc, s34, v1
	s_and_saveexec_b64 s[50:51], vcc
	s_xor_b64 s[50:51], exec, s[50:51]
	s_cbranch_execz .LBB0_1149
	v_lshrrev_b32_e32 v0, 3, v1
	v_lshrrev_b32_e32 v2, 1, v16
	s_movk_i32 s34, 36
	v_mad_u32_u24 v2, v2, s34, v0
	v_and_b32_e32 v0, 7, v1
	v_and_b32_e32 v3, 1, v16
	v_lshl_add_u32 v0, v3, 3, v0
	v_lshl_or_b32 v0, v2, 6, v0

.Lpf_have_m2:
	s_movk_i32 s34, 0x90
	s_waitcnt vmcnt(0)
	v_cmp_gt_i32_e32 vcc, s34, v1
	s_and_saveexec_b64 s[50:51], vcc
	s_xor_b64 s[50:51], exec, s[50:51]
	s_cbranch_execz .LBB0_1250
	v_lshrrev_b32_e32 v0, 3, v1
	s_movk_i32 s34, 18
	v_mad_u32_u24 v2, v16, s34, v0
	v_and_b32_e32 v0, 7, v1
	v_lshl_or_b32 v0, v2, 6, v0
